# GEMM K-loops: block-ending barrier issued two MFMAs early; the next block raises its priority only after its second MFMA so the tail MFMAs win arbitration
# baseline (speedup 1.0000x reference)
; #define PG8_STAGE(bufoff, gbase, voff) do { _Pragma("unroll") for (int _i = 0; _i < 2; ++_i) \
;         __builtin_amdgcn_global_load_lds((const unsigned*)((const char*)(gbase) + (voff)[_i]), (PG8_LAS unsigned*)(lds + (bufoff) + ldsw + _i * 8192), 16, 0, 0); } while (0)
; #define PG8_LDA(dst, b, h) do { _Pragma("unroll") for (int m = 0; m < 4; ++m) _Pragma("unroll") for (int k = 0; k < 2; ++k) dst[m][k] = *(const PG8_LAS bf16x8*)(lds + PG8_SA(b, h) + aoff + m * 2048 + k * 1024); } while (0)
; #define PG8_LDB(dst, b, h) do { _Pragma("unroll") for (int n = 0; n < 2; ++n) _Pragma("unroll") for (int k = 0; k < 2; ++k) dst[n][k] = *(const PG8_LAS bf16x8*)(lds + PG8_SB(b, h) + boff + n * 2048 + k * 1024); } while (0)
; #define PG8_MMA(ai, bj, At, Bt) do { __builtin_amdgcn_s_setprio(1); _Pragma("unroll") for (int m = 0; m < 4; ++m) _Pragma("unroll") for (int n = 0; n < 2; ++n) _Pragma("unroll") for (int k = 0; k < 2; ++k) \
;         acc[ai][bj][m][n] = __builtin_amdgcn_mfma_f32_16x16x32_bf16(Bt[n][k], At[m][k], acc[ai][bj][m][n], 0, 0, 0); __builtin_amdgcn_s_setprio(0); } while (0)
; #define PG8_WAIT_V(n) asm volatile("s_waitcnt vmcnt(" #n ")" ::: "memory")
; #define PG8_WAIT_L(n) asm volatile("s_waitcnt lgkmcnt(" #n ")" ::: "memory")
; #define PG8_BAR __builtin_amdgcn_s_barrier()
; #define PG8_SCHED __builtin_amdgcn_sched_barrier(0)
; template <class Epi, class Sched, bool ALIGN_EPI = false, bool SP2 = false>
; __device__ __forceinline__ void gemm_phase(PG8_LAS unsigned char* lds, const Gemm g, const Sched& S, const Epi& E) {
;     ...
;             const bool last = (t == nt - 2);
;             const char* a1 = cA + (size_t)(t + 1) * kstep;
;             const char* a2 = last ? nA : cA + (size_t)(t + 2) * kstep; const char* b2 = last ? nB : cB + (size_t)(t + 2) * kstep;
;             const char* a3 = a2 + kstep; const char* b3 = b2 + kstep;
;             if (last && has_next) S.a_ready(nxt);
;             if constexpr (SP2) {
;             PG8_LDB(B0, 0, 0); PG8_LDB(B1, 0, 1); PG8_SCHED; PG8_LDA(At, 0, 0); PG8_STAGE(PG8_SA(1, 1), a1 + hstep, voffA);
;             PG8_WAIT_V(8); PG8_WAIT_L(0); PG8_BAR; PG8_MMA(0, 0, At, B0); PG8_MMA(0, 1, At, B1); PG8_BAR; PG8_SCHED;
;             PG8_LDA(At, 0, 1); PG8_STAGE(PG8_SB(0, 0), b2, voffB); PG8_STAGE(PG8_SB(0, 1), b2 + hstep, voffB); PG8_STAGE(PG8_SA(0, 0), a2, voffA);
.LBB0_165:
	s_add_u32 s16, s8, 0xfffc0080
	s_addc_u32 s17, s9, -1
	s_add_i32 s18, 0, 0x10000
	s_cmp_eq_u32 s55, 12
	s_cselect_b32 s43, s14, s17
	s_cselect_b32 s42, s15, s16
	v_add_u32_e32 v0, s18, v194
	s_cselect_b32 s41, s13, s54
	s_cselect_b32 s40, s25, s53
	s_add_i32 s19, 0, 0x14000
	ds_read_b128 v[136:139], v0
	ds_read_b128 v[140:143], v0 offset:1024
	ds_read_b128 v[144:147], v0 offset:2048
	ds_read_b128 v[148:151], v0 offset:3072
	v_add_u32_e32 v0, s19, v194
	ds_read_b128 v[152:155], v0
	ds_read_b128 v[186:189], v0 offset:1024
	ds_read_b128 v[190:193], v0 offset:2048
	ds_read_b128 v[198:201], v0 offset:3072
	v_lshl_add_u64 v[2:3], s[8:9], 0, v[182:183]
	s_add_i32 m0, s45, 0xc000
	ds_read_b128 v[210:213], v196
	ds_read_b128 v[214:217], v196 offset:1024
	ds_read_b128 v[218:221], v196 offset:2048
	ds_read_b128 v[222:225], v196 offset:3072
	ds_read_b128 v[226:229], v196 offset:4096
	ds_read_b128 v[230:233], v196 offset:5120
	ds_read_b128 v[234:237], v196 offset:6144
	ds_read_b128 v[238:241], v196 offset:7168
	global_load_lds_dwordx4 v[2:3], off
	v_lshl_add_u64 v[2:3], s[8:9], 0, v[184:185]
	s_add_i32 m0, s45, 0xe000
	s_nop 0
	global_load_lds_dwordx4 v[2:3], off
	s_waitcnt vmcnt(8)
	s_waitcnt lgkmcnt(0)
	s_barrier
	s_waitcnt lgkmcnt(0)
	v_mfma_f32_16x16x32_bf16 v[132:135], v[136:139], v[210:213], v[132:135]
	v_mfma_f32_16x16x32_bf16 v[128:131], v[144:147], v[210:213], v[128:131]
	s_setprio 1
	v_mfma_f32_16x16x32_bf16 v[124:127], v[136:139], v[218:221], v[124:127]
	v_mfma_f32_16x16x32_bf16 v[120:123], v[144:147], v[218:221], v[120:123]
	v_mfma_f32_16x16x32_bf16 v[116:119], v[136:139], v[226:229], v[116:119]
	v_mfma_f32_16x16x32_bf16 v[112:115], v[144:147], v[226:229], v[112:115]
	v_mfma_f32_16x16x32_bf16 v[108:111], v[136:139], v[234:237], v[108:111]
	v_mfma_f32_16x16x32_bf16 v[104:107], v[144:147], v[234:237], v[104:107]
	v_mfma_f32_16x16x32_bf16 v[132:135], v[140:143], v[214:217], v[132:135]
	v_mfma_f32_16x16x32_bf16 v[128:131], v[148:151], v[214:217], v[128:131]
	v_mfma_f32_16x16x32_bf16 v[124:127], v[140:143], v[222:225], v[124:127]
	v_mfma_f32_16x16x32_bf16 v[120:123], v[148:151], v[222:225], v[120:123]
	v_mfma_f32_16x16x32_bf16 v[116:119], v[140:143], v[230:233], v[116:119]
	v_mfma_f32_16x16x32_bf16 v[112:115], v[148:151], v[230:233], v[112:115]
	v_mfma_f32_16x16x32_bf16 v[108:111], v[140:143], v[238:241], v[108:111]
	v_mfma_f32_16x16x32_bf16 v[104:107], v[148:151], v[238:241], v[104:107]
	s_setprio 0
	s_setprio 1
	v_mfma_f32_16x16x32_bf16 v[84:87], v[152:155], v[210:213], v[84:87]
	v_mfma_f32_16x16x32_bf16 v[76:79], v[190:193], v[210:213], v[76:79]
	v_mfma_f32_16x16x32_bf16 v[68:71], v[152:155], v[218:221], v[68:71]
	v_mfma_f32_16x16x32_bf16 v[64:67], v[190:193], v[218:221], v[64:67]
	v_mfma_f32_16x16x32_bf16 v[52:55], v[152:155], v[226:229], v[52:55]
	v_mfma_f32_16x16x32_bf16 v[48:51], v[190:193], v[226:229], v[48:51]
	v_mfma_f32_16x16x32_bf16 v[44:47], v[152:155], v[234:237], v[44:47]
	v_mfma_f32_16x16x32_bf16 v[40:43], v[190:193], v[234:237], v[40:43]
	v_mfma_f32_16x16x32_bf16 v[84:87], v[186:189], v[214:217], v[84:87]
	v_mfma_f32_16x16x32_bf16 v[76:79], v[198:201], v[214:217], v[76:79]
	v_mfma_f32_16x16x32_bf16 v[68:71], v[186:189], v[222:225], v[68:71]
	v_mfma_f32_16x16x32_bf16 v[64:67], v[198:201], v[222:225], v[64:67]
	v_mfma_f32_16x16x32_bf16 v[52:55], v[186:189], v[230:233], v[52:55]
	v_mfma_f32_16x16x32_bf16 v[48:51], v[198:201], v[230:233], v[48:51]
	s_barrier
	v_mfma_f32_16x16x32_bf16 v[44:47], v[186:189], v[238:241], v[44:47]
	v_mfma_f32_16x16x32_bf16 v[40:43], v[198:201], v[238:241], v[40:43]
	s_setprio 0
	s_add_i32 s16, s18, s44
	v_lshl_add_u64 v[2:3], s[40:41], 0, v[162:163]
	s_mov_b32 m0, s16
	ds_read_b128 v[210:213], v196 offset:16384
	ds_read_b128 v[214:217], v196 offset:17408
	ds_read_b128 v[218:221], v196 offset:18432
	ds_read_b128 v[222:225], v196 offset:19456
	ds_read_b128 v[226:229], v196 offset:20480
	ds_read_b128 v[230:233], v196 offset:21504
	ds_read_b128 v[234:237], v196 offset:22528
	ds_read_b128 v[238:241], v196 offset:23552
	global_load_lds_dwordx4 v[2:3], off
	s_add_i32 m0, s16, 0x2000
	s_add_u32 s16, s40, 0x40000
	v_lshl_add_u64 v[156:157], s[40:41], 0, v[158:159]
	s_addc_u32 s17, s41, 0
	s_add_i32 s18, s19, s44
	global_load_lds_dwordx4 v[156:157], off
	v_lshl_add_u64 v[242:243], s[16:17], 0, v[162:163]
	s_mov_b32 m0, s18
	v_lshl_add_u64 v[244:245], s[42:43], 0, v[160:161]
	global_load_lds_dwordx4 v[242:243], off
	v_lshl_add_u64 v[242:243], s[16:17], 0, v[158:159]
	s_add_i32 m0, s18, 0x2000
	s_nop 0
	global_load_lds_dwordx4 v[242:243], off
	v_lshl_add_u64 v[242:243], s[42:43], 0, v[178:179]
	s_waitcnt vmcnt(6)
	s_waitcnt lgkmcnt(0)
	s_barrier
; #define PG8_STAGE(bufoff, gbase, voff) do { _Pragma("unroll") for (int _i = 0; _i < 2; ++_i) \
;         __builtin_amdgcn_global_load_lds((const unsigned*)((const char*)(gbase) + (voff)[_i]), (PG8_LAS unsigned*)(lds + (bufoff) + ldsw + _i * 8192), 16, 0, 0); } while (0)
; #define PG8_LDA(dst, b, h) do { _Pragma("unroll") for (int m = 0; m < 4; ++m) _Pragma("unroll") for (int k = 0; k < 2; ++k) dst[m][k] = *(const PG8_LAS bf16x8*)(lds + PG8_SA(b, h) + aoff + m * 2048 + k * 1024); } while (0)
; #define PG8_LDB(dst, b, h) do { _Pragma("unroll") for (int n = 0; n < 2; ++n) _Pragma("unroll") for (int k = 0; k < 2; ++k) dst[n][k] = *(const PG8_LAS bf16x8*)(lds + PG8_SB(b, h) + boff + n * 2048 + k * 1024); } while (0)
; #define PG8_MMA(ai, bj, At, Bt) do { __builtin_amdgcn_s_setprio(1); _Pragma("unroll") for (int m = 0; m < 4; ++m) _Pragma("unroll") for (int n = 0; n < 2; ++n) _Pragma("unroll") for (int k = 0; k < 2; ++k) \
;         acc[ai][bj][m][n] = __builtin_amdgcn_mfma_f32_16x16x32_bf16(Bt[n][k], At[m][k], acc[ai][bj][m][n], 0, 0, 0); __builtin_amdgcn_s_setprio(0); } while (0)
; #define PG8_WAIT_V(n) asm volatile("s_waitcnt vmcnt(" #n ")" ::: "memory")
; #define PG8_WAIT_L(n) asm volatile("s_waitcnt lgkmcnt(" #n ")" ::: "memory")
; #define PG8_BAR __builtin_amdgcn_s_barrier()
; #define PG8_SCHED __builtin_amdgcn_sched_barrier(0)
; template <class Epi, class Sched, bool ALIGN_EPI = false, bool SP2 = false>
; __device__ __forceinline__ void gemm_phase(PG8_LAS unsigned char* lds, const Gemm g, const Sched& S, const Epi& E) {
;     ...
;             PG8_WAIT_V(8); PG8_WAIT_L(0); PG8_BAR; PG8_MMA(1, 0, At, B0); PG8_MMA(1, 1, At, B1); PG8_BAR; PG8_SCHED;
;             PG8_LDB(B0, 1, 0); PG8_LDB(B1, 1, 1); PG8_SCHED; PG8_LDA(At, 1, 0); PG8_STAGE(PG8_SA(0, 1), a2 + hstep, voffA);
;             PG8_WAIT_V(8); PG8_WAIT_L(0); PG8_BAR; PG8_MMA(0, 0, At, B0); PG8_MMA(0, 1, At, B1); PG8_BAR; PG8_SCHED;
	s_waitcnt lgkmcnt(0)
	v_mfma_f32_16x16x32_bf16 v[100:103], v[136:139], v[210:213], v[100:103]
	v_mfma_f32_16x16x32_bf16 v[96:99], v[144:147], v[210:213], v[96:99]
	s_setprio 1
	v_mfma_f32_16x16x32_bf16 v[92:95], v[136:139], v[218:221], v[92:95]
	s_mov_b32 m0, s45
	v_mfma_f32_16x16x32_bf16 v[88:91], v[144:147], v[218:221], v[88:91]
	global_load_lds_dwordx4 v[242:243], off
	v_mfma_f32_16x16x32_bf16 v[80:83], v[136:139], v[226:229], v[80:83]
	v_mfma_f32_16x16x32_bf16 v[72:75], v[144:147], v[226:229], v[72:75]
	v_mfma_f32_16x16x32_bf16 v[60:63], v[136:139], v[234:237], v[60:63]
	v_mfma_f32_16x16x32_bf16 v[56:59], v[144:147], v[234:237], v[56:59]
	v_mfma_f32_16x16x32_bf16 v[100:103], v[140:143], v[214:217], v[100:103]
	v_mfma_f32_16x16x32_bf16 v[96:99], v[148:151], v[214:217], v[96:99]
	v_mfma_f32_16x16x32_bf16 v[92:95], v[140:143], v[222:225], v[92:95]
	s_mov_b32 m0, s46
	v_mfma_f32_16x16x32_bf16 v[88:91], v[148:151], v[222:225], v[88:91]
	global_load_lds_dwordx4 v[244:245], off
	v_mfma_f32_16x16x32_bf16 v[80:83], v[140:143], v[230:233], v[80:83]
	v_mfma_f32_16x16x32_bf16 v[72:75], v[148:151], v[230:233], v[72:75]
	v_mfma_f32_16x16x32_bf16 v[60:63], v[140:143], v[238:241], v[60:63]
	v_mfma_f32_16x16x32_bf16 v[56:59], v[148:151], v[238:241], v[56:59]
	s_setprio 0
	s_setprio 1
	v_mfma_f32_16x16x32_bf16 v[36:39], v[152:155], v[210:213], v[36:39]
	v_mfma_f32_16x16x32_bf16 v[32:35], v[190:193], v[210:213], v[32:35]
	v_mfma_f32_16x16x32_bf16 v[28:31], v[152:155], v[218:221], v[28:31]
	v_mfma_f32_16x16x32_bf16 v[24:27], v[190:193], v[218:221], v[24:27]
	v_mfma_f32_16x16x32_bf16 v[20:23], v[152:155], v[226:229], v[20:23]
	v_mfma_f32_16x16x32_bf16 v[16:19], v[190:193], v[226:229], v[16:19]
	v_mfma_f32_16x16x32_bf16 v[12:15], v[152:155], v[234:237], v[12:15]
	v_mfma_f32_16x16x32_bf16 v[8:11], v[190:193], v[234:237], v[8:11]
	v_mfma_f32_16x16x32_bf16 v[36:39], v[186:189], v[214:217], v[36:39]
	v_mfma_f32_16x16x32_bf16 v[32:35], v[198:201], v[214:217], v[32:35]
	v_mfma_f32_16x16x32_bf16 v[28:31], v[186:189], v[222:225], v[28:31]
	v_mfma_f32_16x16x32_bf16 v[24:27], v[198:201], v[222:225], v[24:27]
	v_mfma_f32_16x16x32_bf16 v[20:23], v[186:189], v[230:233], v[20:23]
	v_mfma_f32_16x16x32_bf16 v[16:19], v[198:201], v[230:233], v[16:19]
	s_barrier
	v_mfma_f32_16x16x32_bf16 v[12:15], v[186:189], v[238:241], v[12:15]
	v_mfma_f32_16x16x32_bf16 v[8:11], v[198:201], v[238:241], v[8:11]
	s_setprio 0
	s_add_i32 s18, 0, 0x18000
	v_add_u32_e32 v0, s18, v194
	ds_read_b128 v[136:139], v0
	ds_read_b128 v[140:143], v0 offset:1024
	ds_read_b128 v[144:147], v0 offset:2048
	ds_read_b128 v[148:151], v0 offset:3072
	v_add_u32_e32 v0, s33, v194
	ds_read_b128 v[152:155], v0
	ds_read_b128 v[186:189], v0 offset:1024
	ds_read_b128 v[190:193], v0 offset:2048
	ds_read_b128 v[198:201], v0 offset:3072
	s_add_u32 s16, s42, 0x40000
	s_addc_u32 s17, s43, 0
	s_mov_b32 m0, s47
	v_lshl_add_u64 v[246:247], s[16:17], 0, v[178:179]
	ds_read_b128 v[210:213], v196 offset:32768
	ds_read_b128 v[214:217], v196 offset:33792
	ds_read_b128 v[218:221], v196 offset:34816
	ds_read_b128 v[222:225], v196 offset:35840
	ds_read_b128 v[226:229], v196 offset:36864
	ds_read_b128 v[230:233], v196 offset:37888
	ds_read_b128 v[234:237], v196 offset:38912
	ds_read_b128 v[238:241], v196 offset:39936
	global_load_lds_dwordx4 v[246:247], off
	v_lshl_add_u64 v[246:247], s[16:17], 0, v[160:161]
	s_mov_b32 m0, s48
	s_nop 0
	global_load_lds_dwordx4 v[246:247], off
	s_waitcnt vmcnt(8)
	s_waitcnt lgkmcnt(0)
	s_barrier
	s_waitcnt lgkmcnt(0)
	v_mfma_f32_16x16x32_bf16 v[132:135], v[136:139], v[210:213], v[132:135]
	v_mfma_f32_16x16x32_bf16 v[128:131], v[144:147], v[210:213], v[128:131]
	s_setprio 1
	v_mfma_f32_16x16x32_bf16 v[124:127], v[136:139], v[218:221], v[124:127]
	v_mfma_f32_16x16x32_bf16 v[120:123], v[144:147], v[218:221], v[120:123]
	v_mfma_f32_16x16x32_bf16 v[116:119], v[136:139], v[226:229], v[116:119]
	v_mfma_f32_16x16x32_bf16 v[112:115], v[144:147], v[226:229], v[112:115]
	v_mfma_f32_16x16x32_bf16 v[108:111], v[136:139], v[234:237], v[108:111]
	v_mfma_f32_16x16x32_bf16 v[104:107], v[144:147], v[234:237], v[104:107]
	v_mfma_f32_16x16x32_bf16 v[132:135], v[140:143], v[214:217], v[132:135]
	v_mfma_f32_16x16x32_bf16 v[128:131], v[148:151], v[214:217], v[128:131]
	v_mfma_f32_16x16x32_bf16 v[124:127], v[140:143], v[222:225], v[124:127]
	v_mfma_f32_16x16x32_bf16 v[120:123], v[148:151], v[222:225], v[120:123]
	v_mfma_f32_16x16x32_bf16 v[116:119], v[140:143], v[230:233], v[116:119]
	v_mfma_f32_16x16x32_bf16 v[112:115], v[148:151], v[230:233], v[112:115]
	v_mfma_f32_16x16x32_bf16 v[108:111], v[140:143], v[238:241], v[108:111]
	v_mfma_f32_16x16x32_bf16 v[104:107], v[148:151], v[238:241], v[104:107]
	s_setprio 0
	s_setprio 1
	v_mfma_f32_16x16x32_bf16 v[84:87], v[152:155], v[210:213], v[84:87]
	v_mfma_f32_16x16x32_bf16 v[76:79], v[190:193], v[210:213], v[76:79]
	v_mfma_f32_16x16x32_bf16 v[68:71], v[152:155], v[218:221], v[68:71]
	v_mfma_f32_16x16x32_bf16 v[64:67], v[190:193], v[218:221], v[64:67]
	v_mfma_f32_16x16x32_bf16 v[52:55], v[152:155], v[226:229], v[52:55]
	v_mfma_f32_16x16x32_bf16 v[48:51], v[190:193], v[226:229], v[48:51]
	v_mfma_f32_16x16x32_bf16 v[44:47], v[152:155], v[234:237], v[44:47]
	v_mfma_f32_16x16x32_bf16 v[40:43], v[190:193], v[234:237], v[40:43]
	v_mfma_f32_16x16x32_bf16 v[84:87], v[186:189], v[214:217], v[84:87]
	v_mfma_f32_16x16x32_bf16 v[76:79], v[198:201], v[214:217], v[76:79]
	v_mfma_f32_16x16x32_bf16 v[68:71], v[186:189], v[222:225], v[68:71]
	v_mfma_f32_16x16x32_bf16 v[64:67], v[198:201], v[222:225], v[64:67]
	v_mfma_f32_16x16x32_bf16 v[52:55], v[186:189], v[230:233], v[52:55]
	v_mfma_f32_16x16x32_bf16 v[48:51], v[198:201], v[230:233], v[48:51]
	s_barrier
; #define PG8_STAGE(bufoff, gbase, voff) do { _Pragma("unroll") for (int _i = 0; _i < 2; ++_i) \
;         __builtin_amdgcn_global_load_lds((const unsigned*)((const char*)(gbase) + (voff)[_i]), (PG8_LAS unsigned*)(lds + (bufoff) + ldsw + _i * 8192), 16, 0, 0); } while (0)
; #define PG8_LDA(dst, b, h) do { _Pragma("unroll") for (int m = 0; m < 4; ++m) _Pragma("unroll") for (int k = 0; k < 2; ++k) dst[m][k] = *(const PG8_LAS bf16x8*)(lds + PG8_SA(b, h) + aoff + m * 2048 + k * 1024); } while (0)
; #define PG8_MMA(ai, bj, At, Bt) do { __builtin_amdgcn_s_setprio(1); _Pragma("unroll") for (int m = 0; m < 4; ++m) _Pragma("unroll") for (int n = 0; n < 2; ++n) _Pragma("unroll") for (int k = 0; k < 2; ++k) \
;         acc[ai][bj][m][n] = __builtin_amdgcn_mfma_f32_16x16x32_bf16(Bt[n][k], At[m][k], acc[ai][bj][m][n], 0, 0, 0); __builtin_amdgcn_s_setprio(0); } while (0)
; #define PG8_WAIT_V(n) asm volatile("s_waitcnt vmcnt(" #n ")" ::: "memory")
; #define PG8_WAIT_L(n) asm volatile("s_waitcnt lgkmcnt(" #n ")" ::: "memory")
; #define PG8_BAR __builtin_amdgcn_s_barrier()
; #define PG8_SCHED __builtin_amdgcn_sched_barrier(0)
; template <class Epi, class Sched, bool ALIGN_EPI = false, bool SP2 = false>
; __device__ __forceinline__ void gemm_phase(PG8_LAS unsigned char* lds, const Gemm g, const Sched& S, const Epi& E) {
;     ...
;             PG8_WAIT_V(8); PG8_WAIT_L(0); PG8_BAR; PG8_MMA(0, 0, At, B0); PG8_MMA(0, 1, At, B1); PG8_BAR; PG8_SCHED;
;             PG8_LDA(At, 1, 1); PG8_STAGE(PG8_SB(1, 0), b3, voffB); PG8_STAGE(PG8_SB(1, 1), b3 + hstep, voffB); PG8_STAGE(PG8_SA(1, 0), a3, voffA);
;             PG8_WAIT_V(8); PG8_WAIT_L(0); PG8_BAR; PG8_MMA(1, 0, At, B0); PG8_MMA(1, 1, At, B1); PG8_BAR; PG8_SCHED;
	v_mfma_f32_16x16x32_bf16 v[44:47], v[186:189], v[238:241], v[44:47]
	v_mfma_f32_16x16x32_bf16 v[40:43], v[198:201], v[238:241], v[40:43]
	s_setprio 0
	s_add_i32 s16, s18, s44
	v_lshl_add_u64 v[2:3], v[2:3], 0, s[20:21]
	s_mov_b32 m0, s16
	ds_read_b128 v[210:213], v196 offset:49152
	ds_read_b128 v[214:217], v196 offset:50176
	ds_read_b128 v[218:221], v196 offset:51200
	ds_read_b128 v[222:225], v196 offset:52224
	ds_read_b128 v[226:229], v196 offset:53248
	ds_read_b128 v[230:233], v196 offset:54272
	ds_read_b128 v[234:237], v196 offset:55296
	ds_read_b128 v[238:241], v196 offset:56320
	global_load_lds_dwordx4 v[2:3], off
	s_add_i32 m0, s16, 0x2000
	s_add_u32 s16, s40, 0x40080
	v_lshl_add_u64 v[2:3], v[156:157], 0, s[20:21]
	s_addc_u32 s17, s41, 0
	s_add_i32 s18, s33, s44
	global_load_lds_dwordx4 v[2:3], off
	v_lshl_add_u64 v[2:3], s[16:17], 0, v[162:163]
	s_mov_b32 m0, s18
	s_nop 0
	global_load_lds_dwordx4 v[2:3], off
	v_lshl_add_u64 v[2:3], s[16:17], 0, v[158:159]
	s_add_i32 m0, s18, 0x2000
	s_nop 0
	global_load_lds_dwordx4 v[2:3], off
	v_lshl_add_u64 v[2:3], v[242:243], 0, s[20:21]
	v_lshl_add_u64 v[244:245], v[244:245], 0, s[20:21]
	s_waitcnt vmcnt(6)
	s_waitcnt lgkmcnt(0)
	s_barrier
	s_waitcnt lgkmcnt(0)
	v_mfma_f32_16x16x32_bf16 v[100:103], v[136:139], v[210:213], v[100:103]
	v_mfma_f32_16x16x32_bf16 v[96:99], v[144:147], v[210:213], v[96:99]
	s_setprio 1
	v_mfma_f32_16x16x32_bf16 v[92:95], v[136:139], v[218:221], v[92:95]
	s_mov_b32 m0, s49
	v_mfma_f32_16x16x32_bf16 v[88:91], v[144:147], v[218:221], v[88:91]
	global_load_lds_dwordx4 v[2:3], off
	v_mfma_f32_16x16x32_bf16 v[80:83], v[136:139], v[226:229], v[80:83]
	v_mfma_f32_16x16x32_bf16 v[72:75], v[144:147], v[226:229], v[72:75]
	v_mfma_f32_16x16x32_bf16 v[60:63], v[136:139], v[234:237], v[60:63]
	v_mfma_f32_16x16x32_bf16 v[56:59], v[144:147], v[234:237], v[56:59]
	v_mfma_f32_16x16x32_bf16 v[100:103], v[140:143], v[214:217], v[100:103]
	v_mfma_f32_16x16x32_bf16 v[96:99], v[148:151], v[214:217], v[96:99]
	v_mfma_f32_16x16x32_bf16 v[92:95], v[140:143], v[222:225], v[92:95]
	s_mov_b32 m0, s50
	v_mfma_f32_16x16x32_bf16 v[88:91], v[148:151], v[222:225], v[88:91]
	global_load_lds_dwordx4 v[244:245], off
	v_mfma_f32_16x16x32_bf16 v[80:83], v[140:143], v[230:233], v[80:83]
	v_mfma_f32_16x16x32_bf16 v[72:75], v[148:151], v[230:233], v[72:75]
	v_mfma_f32_16x16x32_bf16 v[60:63], v[140:143], v[238:241], v[60:63]
	v_mfma_f32_16x16x32_bf16 v[56:59], v[148:151], v[238:241], v[56:59]
	s_setprio 0
	s_setprio 1
	v_mfma_f32_16x16x32_bf16 v[36:39], v[152:155], v[210:213], v[36:39]
	v_mfma_f32_16x16x32_bf16 v[32:35], v[190:193], v[210:213], v[32:35]
	v_mfma_f32_16x16x32_bf16 v[28:31], v[152:155], v[218:221], v[28:31]
	v_mfma_f32_16x16x32_bf16 v[24:27], v[190:193], v[218:221], v[24:27]
	v_mfma_f32_16x16x32_bf16 v[20:23], v[152:155], v[226:229], v[20:23]
	v_mfma_f32_16x16x32_bf16 v[16:19], v[190:193], v[226:229], v[16:19]
	v_mfma_f32_16x16x32_bf16 v[12:15], v[152:155], v[234:237], v[12:15]
	v_mfma_f32_16x16x32_bf16 v[8:11], v[190:193], v[234:237], v[8:11]
	v_mfma_f32_16x16x32_bf16 v[36:39], v[186:189], v[214:217], v[36:39]
	v_mfma_f32_16x16x32_bf16 v[32:35], v[198:201], v[214:217], v[32:35]
	v_mfma_f32_16x16x32_bf16 v[28:31], v[186:189], v[222:225], v[28:31]
	v_mfma_f32_16x16x32_bf16 v[24:27], v[198:201], v[222:225], v[24:27]
	v_mfma_f32_16x16x32_bf16 v[20:23], v[186:189], v[230:233], v[20:23]
	v_mfma_f32_16x16x32_bf16 v[16:19], v[198:201], v[230:233], v[16:19]
	s_barrier
	v_mfma_f32_16x16x32_bf16 v[12:15], v[186:189], v[238:241], v[12:15]
	v_mfma_f32_16x16x32_bf16 v[8:11], v[198:201], v[238:241], v[8:11]
	s_setprio 0
	s_add_i32 s55, s55, 2
	s_add_u32 s8, s8, 0x100
	s_addc_u32 s9, s9, 0
	s_add_u32 s53, s53, 0x100
	s_addc_u32 s54, s54, 0
	s_cmp_gt_u32 s55, 13
	s_cbranch_scc0 .LBB0_165
	s_and_b64 vcc, exec, s[10:11]
	s_cbranch_vccz .LBB0_168
	s_barrier
	s_setprio 1

; #define PG8_STAGE(bufoff, gbase, voff) do { _Pragma("unroll") for (int _i = 0; _i < 2; ++_i) \
;         __builtin_amdgcn_global_load_lds((const unsigned*)((const char*)(gbase) + (voff)[_i]), (PG8_LAS unsigned*)(lds + (bufoff) + ldsw + _i * 8192), 16, 0, 0); } while (0)
; #define PG8_LDA(dst, b, h) do { _Pragma("unroll") for (int m = 0; m < 4; ++m) _Pragma("unroll") for (int k = 0; k < 2; ++k) dst[m][k] = *(const PG8_LAS bf16x8*)(lds + PG8_SA(b, h) + aoff + m * 2048 + k * 1024); } while (0)
; #define PG8_LDB(dst, b, h) do { _Pragma("unroll") for (int n = 0; n < 2; ++n) _Pragma("unroll") for (int k = 0; k < 2; ++k) dst[n][k] = *(const PG8_LAS bf16x8*)(lds + PG8_SB(b, h) + boff + n * 2048 + k * 1024); } while (0)
; #define PG8_MMA(ai, bj, At, Bt) do { __builtin_amdgcn_s_setprio(1); _Pragma("unroll") for (int m = 0; m < 4; ++m) _Pragma("unroll") for (int n = 0; n < 2; ++n) _Pragma("unroll") for (int k = 0; k < 2; ++k) \
;         acc[ai][bj][m][n] = __builtin_amdgcn_mfma_f32_16x16x32_bf16(Bt[n][k], At[m][k], acc[ai][bj][m][n], 0, 0, 0); __builtin_amdgcn_s_setprio(0); } while (0)
; #define PG8_WAIT_V(n) asm volatile("s_waitcnt vmcnt(" #n ")" ::: "memory")
; template <class Epi, class Sched, bool ALIGN_EPI = false, bool SP2 = false>
; __device__ __forceinline__ void gemm_phase(PG8_LAS unsigned char* lds, const Gemm g, const Sched& S, const Epi& E) {
;     ...
;         const char* nA = has_next ? (const char*)g.A + (size_t)nxt.pm * tstep : cA; const char* nB = has_next ? (const char*)g.Bt + (size_t)nxt.pn * tstep : cB;
;         for (int t = 0; t < nt; t += 2) {
;             const bool last = (t == nt - 2);
;             const char* a1 = cA + (size_t)(t + 1) * kstep;
;             const char* a2 = last ? nA : cA + (size_t)(t + 2) * kstep; const char* b2 = last ? nB : cB + (size_t)(t + 2) * kstep;
;             const char* a3 = a2 + kstep; const char* b3 = b2 + kstep;
;             if (last && has_next) S.a_ready(nxt);
;             if constexpr (SP2) {
;             PG8_LDB(B0, 0, 0); PG8_LDB(B1, 0, 1); PG8_SCHED; PG8_LDA(At, 0, 0); PG8_STAGE(PG8_SA(1, 1), a1 + hstep, voffA);
;             PG8_WAIT_V(8); PG8_WAIT_L(0); PG8_BAR; PG8_MMA(0, 0, At, B0); PG8_MMA(0, 1, At, B1); PG8_BAR; PG8_SCHED;
;             PG8_LDA(At, 0, 1); PG8_STAGE(PG8_SB(0, 0), b2, voffB); PG8_STAGE(PG8_SB(0, 1), b2 + hstep, voffB); PG8_STAGE(PG8_SA(0, 0), a2, voffA);
.LBB0_203:
	s_add_i32 s36, s28, 2
	s_add_u32 s16, s24, 0x80
	s_addc_u32 s17, s25, 0
	s_add_i32 s18, 0, 0x10000
	s_cmp_eq_u32 s60, s28
	s_cselect_b32 s29, s3, s17
	s_cselect_b32 s28, s2, s16
	v_add_u32_e32 v137, s18, v200
	s_cselect_b32 s17, s9, s35
	s_cselect_b32 s16, s8, s23
	s_add_i32 s19, 0, 0x14000
	ds_read_b128 v[144:147], v137
	ds_read_b128 v[148:151], v137 offset:1024
	ds_read_b128 v[152:155], v137 offset:2048
	ds_read_b128 v[156:159], v137 offset:3072
	v_add_u32_e32 v137, s19, v200
	ds_read_b128 v[160:163], v137
	ds_read_b128 v[178:181], v137 offset:1024
	ds_read_b128 v[182:185], v137 offset:2048
	ds_read_b128 v[186:189], v137 offset:3072
	v_lshl_add_u64 v[198:199], s[24:25], 0, v[140:141]
	s_add_i32 m0, s52, 0xc000
	ds_read_b128 v[190:193], v210
	ds_read_b128 v[194:197], v210 offset:1024
	ds_read_b128 v[212:215], v210 offset:2048
	ds_read_b128 v[216:219], v210 offset:3072
	ds_read_b128 v[220:223], v210 offset:4096
	ds_read_b128 v[224:227], v210 offset:5120
	ds_read_b128 v[228:231], v210 offset:6144
	ds_read_b128 v[232:235], v210 offset:7168
	global_load_lds_dwordx4 v[198:199], off
	v_lshl_add_u64 v[198:199], s[24:25], 0, v[142:143]
	s_add_i32 m0, s52, 0xe000
	s_nop 0
	global_load_lds_dwordx4 v[198:199], off
	s_waitcnt vmcnt(8)
	s_waitcnt lgkmcnt(0)
	s_barrier
	s_waitcnt lgkmcnt(0)
	v_mfma_f32_16x16x32_bf16 v[132:135], v[144:147], v[190:193], v[132:135]
	v_mfma_f32_16x16x32_bf16 v[128:131], v[152:155], v[190:193], v[128:131]
	s_setprio 1
	v_mfma_f32_16x16x32_bf16 v[116:119], v[144:147], v[212:215], v[116:119]
	v_mfma_f32_16x16x32_bf16 v[112:115], v[152:155], v[212:215], v[112:115]
	v_mfma_f32_16x16x32_bf16 v[100:103], v[144:147], v[220:223], v[100:103]
	v_mfma_f32_16x16x32_bf16 v[96:99], v[152:155], v[220:223], v[96:99]
	v_mfma_f32_16x16x32_bf16 v[84:87], v[144:147], v[228:231], v[84:87]
	v_mfma_f32_16x16x32_bf16 v[80:83], v[152:155], v[228:231], v[80:83]
	v_mfma_f32_16x16x32_bf16 v[132:135], v[148:151], v[194:197], v[132:135]
	v_mfma_f32_16x16x32_bf16 v[128:131], v[156:159], v[194:197], v[128:131]
	v_mfma_f32_16x16x32_bf16 v[116:119], v[148:151], v[216:219], v[116:119]
	v_mfma_f32_16x16x32_bf16 v[112:115], v[156:159], v[216:219], v[112:115]
	v_mfma_f32_16x16x32_bf16 v[100:103], v[148:151], v[224:227], v[100:103]
	v_mfma_f32_16x16x32_bf16 v[96:99], v[156:159], v[224:227], v[96:99]
	v_mfma_f32_16x16x32_bf16 v[84:87], v[148:151], v[232:235], v[84:87]
	v_mfma_f32_16x16x32_bf16 v[80:83], v[156:159], v[232:235], v[80:83]
	s_setprio 0
	s_setprio 1
	v_mfma_f32_16x16x32_bf16 v[124:127], v[160:163], v[190:193], v[124:127]
	v_mfma_f32_16x16x32_bf16 v[120:123], v[182:185], v[190:193], v[120:123]
	v_mfma_f32_16x16x32_bf16 v[108:111], v[160:163], v[212:215], v[108:111]
	v_mfma_f32_16x16x32_bf16 v[104:107], v[182:185], v[212:215], v[104:107]
	v_mfma_f32_16x16x32_bf16 v[92:95], v[160:163], v[220:223], v[92:95]
	v_mfma_f32_16x16x32_bf16 v[88:91], v[182:185], v[220:223], v[88:91]
	v_mfma_f32_16x16x32_bf16 v[76:79], v[160:163], v[228:231], v[76:79]
	v_mfma_f32_16x16x32_bf16 v[72:75], v[182:185], v[228:231], v[72:75]
	v_mfma_f32_16x16x32_bf16 v[124:127], v[178:181], v[194:197], v[124:127]
	v_mfma_f32_16x16x32_bf16 v[120:123], v[186:189], v[194:197], v[120:123]
	v_mfma_f32_16x16x32_bf16 v[108:111], v[178:181], v[216:219], v[108:111]
	v_mfma_f32_16x16x32_bf16 v[104:107], v[186:189], v[216:219], v[104:107]
	v_mfma_f32_16x16x32_bf16 v[92:95], v[178:181], v[224:227], v[92:95]
	v_mfma_f32_16x16x32_bf16 v[88:91], v[186:189], v[224:227], v[88:91]
	s_barrier
	v_mfma_f32_16x16x32_bf16 v[76:79], v[178:181], v[232:235], v[76:79]
	v_mfma_f32_16x16x32_bf16 v[72:75], v[186:189], v[232:235], v[72:75]
	s_setprio 0
	s_add_i32 s18, s18, s41
	v_lshl_add_u64 v[198:199], s[16:17], 0, v[0:1]
	s_mov_b32 m0, s18
	ds_read_b128 v[190:193], v210 offset:16384
	ds_read_b128 v[194:197], v210 offset:17408
	ds_read_b128 v[212:215], v210 offset:18432
	ds_read_b128 v[216:219], v210 offset:19456
	ds_read_b128 v[220:223], v210 offset:20480
	ds_read_b128 v[224:227], v210 offset:21504
	ds_read_b128 v[228:231], v210 offset:22528
	ds_read_b128 v[232:235], v210 offset:23552
	global_load_lds_dwordx4 v[198:199], off
	s_add_i32 m0, s18, 0x2000
	v_lshl_add_u64 v[236:237], s[16:17], 0, v[2:3]
	s_add_u32 s16, s16, s12
	s_addc_u32 s17, s17, 0
	s_add_i32 s18, s19, s41
	global_load_lds_dwordx4 v[236:237], off
	v_lshl_add_u64 v[238:239], s[16:17], 0, v[0:1]
	s_mov_b32 m0, s18
	v_lshl_add_u64 v[240:241], s[16:17], 0, v[2:3]
	global_load_lds_dwordx4 v[238:239], off
	s_add_i32 m0, s18, 0x2000
	v_lshl_add_u64 v[242:243], s[28:29], 0, v[0:1]
	global_load_lds_dwordx4 v[240:241], off
	v_lshl_add_u64 v[244:245], s[28:29], 0, v[2:3]
	s_waitcnt vmcnt(6)
	s_waitcnt lgkmcnt(0)
	s_barrier
; #define PG8_STAGE(bufoff, gbase, voff) do { _Pragma("unroll") for (int _i = 0; _i < 2; ++_i) \
;         __builtin_amdgcn_global_load_lds((const unsigned*)((const char*)(gbase) + (voff)[_i]), (PG8_LAS unsigned*)(lds + (bufoff) + ldsw + _i * 8192), 16, 0, 0); } while (0)
; #define PG8_LDA(dst, b, h) do { _Pragma("unroll") for (int m = 0; m < 4; ++m) _Pragma("unroll") for (int k = 0; k < 2; ++k) dst[m][k] = *(const PG8_LAS bf16x8*)(lds + PG8_SA(b, h) + aoff + m * 2048 + k * 1024); } while (0)
; #define PG8_LDB(dst, b, h) do { _Pragma("unroll") for (int n = 0; n < 2; ++n) _Pragma("unroll") for (int k = 0; k < 2; ++k) dst[n][k] = *(const PG8_LAS bf16x8*)(lds + PG8_SB(b, h) + boff + n * 2048 + k * 1024); } while (0)
; #define PG8_MMA(ai, bj, At, Bt) do { __builtin_amdgcn_s_setprio(1); _Pragma("unroll") for (int m = 0; m < 4; ++m) _Pragma("unroll") for (int n = 0; n < 2; ++n) _Pragma("unroll") for (int k = 0; k < 2; ++k) \
;         acc[ai][bj][m][n] = __builtin_amdgcn_mfma_f32_16x16x32_bf16(Bt[n][k], At[m][k], acc[ai][bj][m][n], 0, 0, 0); __builtin_amdgcn_s_setprio(0); } while (0)
; #define PG8_WAIT_V(n) asm volatile("s_waitcnt vmcnt(" #n ")" ::: "memory")
; #define PG8_WAIT_L(n) asm volatile("s_waitcnt lgkmcnt(" #n ")" ::: "memory")
; #define PG8_BAR __builtin_amdgcn_s_barrier()
; #define PG8_SCHED __builtin_amdgcn_sched_barrier(0)
; template <class Epi, class Sched, bool ALIGN_EPI = false, bool SP2 = false>
; __device__ __forceinline__ void gemm_phase(PG8_LAS unsigned char* lds, const Gemm g, const Sched& S, const Epi& E) {
;     ...
;             PG8_WAIT_V(8); PG8_WAIT_L(0); PG8_BAR; PG8_MMA(1, 0, At, B0); PG8_MMA(1, 1, At, B1); PG8_BAR; PG8_SCHED;
;             PG8_LDB(B0, 1, 0); PG8_LDB(B1, 1, 1); PG8_SCHED; PG8_LDA(At, 1, 0); PG8_STAGE(PG8_SA(0, 1), a2 + hstep, voffA);
;             PG8_WAIT_V(8); PG8_WAIT_L(0); PG8_BAR; PG8_MMA(0, 0, At, B0); PG8_MMA(0, 1, At, B1); PG8_BAR; PG8_SCHED;
	s_waitcnt lgkmcnt(0)
	v_mfma_f32_16x16x32_bf16 v[68:71], v[144:147], v[190:193], v[68:71]
	v_mfma_f32_16x16x32_bf16 v[64:67], v[152:155], v[190:193], v[64:67]
	s_setprio 1
	v_mfma_f32_16x16x32_bf16 v[52:55], v[144:147], v[212:215], v[52:55]
	s_mov_b32 m0, s52
	v_mfma_f32_16x16x32_bf16 v[48:51], v[152:155], v[212:215], v[48:51]
	global_load_lds_dwordx4 v[242:243], off
	v_mfma_f32_16x16x32_bf16 v[36:39], v[144:147], v[220:223], v[36:39]
	v_mfma_f32_16x16x32_bf16 v[32:35], v[152:155], v[220:223], v[32:35]
	v_mfma_f32_16x16x32_bf16 v[20:23], v[144:147], v[228:231], v[20:23]
	v_mfma_f32_16x16x32_bf16 v[16:19], v[152:155], v[228:231], v[16:19]
	v_mfma_f32_16x16x32_bf16 v[68:71], v[148:151], v[194:197], v[68:71]
	v_mfma_f32_16x16x32_bf16 v[64:67], v[156:159], v[194:197], v[64:67]
	v_mfma_f32_16x16x32_bf16 v[52:55], v[148:151], v[216:219], v[52:55]
	s_mov_b32 m0, s53
	v_mfma_f32_16x16x32_bf16 v[48:51], v[156:159], v[216:219], v[48:51]
	global_load_lds_dwordx4 v[244:245], off
	v_mfma_f32_16x16x32_bf16 v[36:39], v[148:151], v[224:227], v[36:39]
	v_mfma_f32_16x16x32_bf16 v[32:35], v[156:159], v[224:227], v[32:35]
	v_mfma_f32_16x16x32_bf16 v[20:23], v[148:151], v[232:235], v[20:23]
	v_mfma_f32_16x16x32_bf16 v[16:19], v[156:159], v[232:235], v[16:19]
	s_setprio 0
	s_setprio 1
	v_mfma_f32_16x16x32_bf16 v[60:63], v[160:163], v[190:193], v[60:63]
	v_mfma_f32_16x16x32_bf16 v[56:59], v[182:185], v[190:193], v[56:59]
	v_mfma_f32_16x16x32_bf16 v[44:47], v[160:163], v[212:215], v[44:47]
	v_mfma_f32_16x16x32_bf16 v[40:43], v[182:185], v[212:215], v[40:43]
	v_mfma_f32_16x16x32_bf16 v[28:31], v[160:163], v[220:223], v[28:31]
	v_mfma_f32_16x16x32_bf16 v[24:27], v[182:185], v[220:223], v[24:27]
	v_mfma_f32_16x16x32_bf16 v[12:15], v[160:163], v[228:231], v[12:15]
	v_mfma_f32_16x16x32_bf16 v[8:11], v[182:185], v[228:231], v[8:11]
	v_mfma_f32_16x16x32_bf16 v[60:63], v[178:181], v[194:197], v[60:63]
	v_mfma_f32_16x16x32_bf16 v[56:59], v[186:189], v[194:197], v[56:59]
	v_mfma_f32_16x16x32_bf16 v[44:47], v[178:181], v[216:219], v[44:47]
	v_mfma_f32_16x16x32_bf16 v[40:43], v[186:189], v[216:219], v[40:43]
	v_mfma_f32_16x16x32_bf16 v[28:31], v[178:181], v[224:227], v[28:31]
	v_mfma_f32_16x16x32_bf16 v[24:27], v[186:189], v[224:227], v[24:27]
	s_barrier
	v_mfma_f32_16x16x32_bf16 v[12:15], v[178:181], v[232:235], v[12:15]
	v_mfma_f32_16x16x32_bf16 v[8:11], v[186:189], v[232:235], v[8:11]
	s_setprio 0
	s_add_i32 s18, 0, 0x18000
	v_add_u32_e32 v137, s18, v200
	ds_read_b128 v[144:147], v137
	ds_read_b128 v[148:151], v137 offset:1024
	ds_read_b128 v[152:155], v137 offset:2048
	ds_read_b128 v[156:159], v137 offset:3072
	v_add_u32_e32 v137, s33, v200
	ds_read_b128 v[160:163], v137
	ds_read_b128 v[178:181], v137 offset:1024
	ds_read_b128 v[182:185], v137 offset:2048
	ds_read_b128 v[186:189], v137 offset:3072
	s_add_u32 s16, s28, s12
	s_addc_u32 s17, s29, 0
	s_mov_b32 m0, s54
	v_lshl_add_u64 v[246:247], s[16:17], 0, v[0:1]
	ds_read_b128 v[190:193], v210 offset:32768
	ds_read_b128 v[194:197], v210 offset:33792
	ds_read_b128 v[212:215], v210 offset:34816
	ds_read_b128 v[216:219], v210 offset:35840
	ds_read_b128 v[220:223], v210 offset:36864
	ds_read_b128 v[224:227], v210 offset:37888
	ds_read_b128 v[228:231], v210 offset:38912
	ds_read_b128 v[232:235], v210 offset:39936
	global_load_lds_dwordx4 v[246:247], off
	v_lshl_add_u64 v[246:247], s[16:17], 0, v[2:3]
	s_mov_b32 m0, s55
	s_nop 0
	global_load_lds_dwordx4 v[246:247], off
	s_waitcnt vmcnt(8)
	s_waitcnt lgkmcnt(0)
	s_barrier
	s_waitcnt lgkmcnt(0)
	v_mfma_f32_16x16x32_bf16 v[132:135], v[144:147], v[190:193], v[132:135]
	v_mfma_f32_16x16x32_bf16 v[128:131], v[152:155], v[190:193], v[128:131]
	s_setprio 1
	v_mfma_f32_16x16x32_bf16 v[116:119], v[144:147], v[212:215], v[116:119]
	v_mfma_f32_16x16x32_bf16 v[112:115], v[152:155], v[212:215], v[112:115]
	v_mfma_f32_16x16x32_bf16 v[100:103], v[144:147], v[220:223], v[100:103]
	v_mfma_f32_16x16x32_bf16 v[96:99], v[152:155], v[220:223], v[96:99]
	v_mfma_f32_16x16x32_bf16 v[84:87], v[144:147], v[228:231], v[84:87]
	v_mfma_f32_16x16x32_bf16 v[80:83], v[152:155], v[228:231], v[80:83]
	v_mfma_f32_16x16x32_bf16 v[132:135], v[148:151], v[194:197], v[132:135]
	v_mfma_f32_16x16x32_bf16 v[128:131], v[156:159], v[194:197], v[128:131]
	v_mfma_f32_16x16x32_bf16 v[116:119], v[148:151], v[216:219], v[116:119]
	v_mfma_f32_16x16x32_bf16 v[112:115], v[156:159], v[216:219], v[112:115]
	v_mfma_f32_16x16x32_bf16 v[100:103], v[148:151], v[224:227], v[100:103]
	v_mfma_f32_16x16x32_bf16 v[96:99], v[156:159], v[224:227], v[96:99]
	v_mfma_f32_16x16x32_bf16 v[84:87], v[148:151], v[232:235], v[84:87]
	v_mfma_f32_16x16x32_bf16 v[80:83], v[156:159], v[232:235], v[80:83]
	s_setprio 0
	s_setprio 1
	v_mfma_f32_16x16x32_bf16 v[124:127], v[160:163], v[190:193], v[124:127]
	v_mfma_f32_16x16x32_bf16 v[120:123], v[182:185], v[190:193], v[120:123]
	v_mfma_f32_16x16x32_bf16 v[108:111], v[160:163], v[212:215], v[108:111]
	v_mfma_f32_16x16x32_bf16 v[104:107], v[182:185], v[212:215], v[104:107]
	v_mfma_f32_16x16x32_bf16 v[92:95], v[160:163], v[220:223], v[92:95]
	v_mfma_f32_16x16x32_bf16 v[88:91], v[182:185], v[220:223], v[88:91]
	v_mfma_f32_16x16x32_bf16 v[76:79], v[160:163], v[228:231], v[76:79]
	v_mfma_f32_16x16x32_bf16 v[72:75], v[182:185], v[228:231], v[72:75]
	v_mfma_f32_16x16x32_bf16 v[124:127], v[178:181], v[194:197], v[124:127]
	v_mfma_f32_16x16x32_bf16 v[120:123], v[186:189], v[194:197], v[120:123]
	v_mfma_f32_16x16x32_bf16 v[108:111], v[178:181], v[216:219], v[108:111]
	v_mfma_f32_16x16x32_bf16 v[104:107], v[186:189], v[216:219], v[104:107]
	v_mfma_f32_16x16x32_bf16 v[92:95], v[178:181], v[224:227], v[92:95]
	v_mfma_f32_16x16x32_bf16 v[88:91], v[186:189], v[224:227], v[88:91]
	s_barrier
; #define PG8_STAGE(bufoff, gbase, voff) do { _Pragma("unroll") for (int _i = 0; _i < 2; ++_i) \
;         __builtin_amdgcn_global_load_lds((const unsigned*)((const char*)(gbase) + (voff)[_i]), (PG8_LAS unsigned*)(lds + (bufoff) + ldsw + _i * 8192), 16, 0, 0); } while (0)
; #define PG8_LDA(dst, b, h) do { _Pragma("unroll") for (int m = 0; m < 4; ++m) _Pragma("unroll") for (int k = 0; k < 2; ++k) dst[m][k] = *(const PG8_LAS bf16x8*)(lds + PG8_SA(b, h) + aoff + m * 2048 + k * 1024); } while (0)
; #define PG8_MMA(ai, bj, At, Bt) do { __builtin_amdgcn_s_setprio(1); _Pragma("unroll") for (int m = 0; m < 4; ++m) _Pragma("unroll") for (int n = 0; n < 2; ++n) _Pragma("unroll") for (int k = 0; k < 2; ++k) \
;         acc[ai][bj][m][n] = __builtin_amdgcn_mfma_f32_16x16x32_bf16(Bt[n][k], At[m][k], acc[ai][bj][m][n], 0, 0, 0); __builtin_amdgcn_s_setprio(0); } while (0)
; #define PG8_WAIT_V(n) asm volatile("s_waitcnt vmcnt(" #n ")" ::: "memory")
; #define PG8_WAIT_L(n) asm volatile("s_waitcnt lgkmcnt(" #n ")" ::: "memory")
; #define PG8_BAR __builtin_amdgcn_s_barrier()
; #define PG8_SCHED __builtin_amdgcn_sched_barrier(0)
; template <class Epi, class Sched, bool ALIGN_EPI = false, bool SP2 = false>
; __device__ __forceinline__ void gemm_phase(PG8_LAS unsigned char* lds, const Gemm g, const Sched& S, const Epi& E) {
;     ...
;             PG8_WAIT_V(8); PG8_WAIT_L(0); PG8_BAR; PG8_MMA(0, 0, At, B0); PG8_MMA(0, 1, At, B1); PG8_BAR; PG8_SCHED;
;             PG8_LDA(At, 1, 1); PG8_STAGE(PG8_SB(1, 0), b3, voffB); PG8_STAGE(PG8_SB(1, 1), b3 + hstep, voffB); PG8_STAGE(PG8_SA(1, 0), a3, voffA);
;             PG8_WAIT_V(8); PG8_WAIT_L(0); PG8_BAR; PG8_MMA(1, 0, At, B0); PG8_MMA(1, 1, At, B1); PG8_BAR; PG8_SCHED;
	v_mfma_f32_16x16x32_bf16 v[76:79], v[178:181], v[232:235], v[76:79]
	v_mfma_f32_16x16x32_bf16 v[72:75], v[186:189], v[232:235], v[72:75]
	s_setprio 0
	s_add_i32 s16, s18, s41
	v_lshl_add_u64 v[198:199], v[198:199], 0, s[20:21]
	s_mov_b32 m0, s16
	ds_read_b128 v[190:193], v210 offset:49152
	ds_read_b128 v[194:197], v210 offset:50176
	ds_read_b128 v[212:215], v210 offset:51200
	ds_read_b128 v[216:219], v210 offset:52224
	ds_read_b128 v[220:223], v210 offset:53248
	ds_read_b128 v[224:227], v210 offset:54272
	ds_read_b128 v[228:231], v210 offset:55296
	ds_read_b128 v[232:235], v210 offset:56320
	global_load_lds_dwordx4 v[198:199], off
	v_lshl_add_u64 v[198:199], v[236:237], 0, s[20:21]
	s_add_i32 m0, s16, 0x2000
	s_add_i32 s16, s33, s41
	global_load_lds_dwordx4 v[198:199], off
	v_lshl_add_u64 v[198:199], v[238:239], 0, s[20:21]
	s_mov_b32 m0, s16
	s_nop 0
	global_load_lds_dwordx4 v[198:199], off
	v_lshl_add_u64 v[198:199], v[240:241], 0, s[20:21]
	s_add_i32 m0, s16, 0x2000
	s_nop 0
	global_load_lds_dwordx4 v[198:199], off
	v_lshl_add_u64 v[198:199], v[242:243], 0, s[20:21]
	v_lshl_add_u64 v[244:245], v[244:245], 0, s[20:21]
	s_waitcnt vmcnt(6)
	s_waitcnt lgkmcnt(0)
	s_barrier
	s_waitcnt lgkmcnt(0)
	v_mfma_f32_16x16x32_bf16 v[68:71], v[144:147], v[190:193], v[68:71]
	v_mfma_f32_16x16x32_bf16 v[64:67], v[152:155], v[190:193], v[64:67]
	s_setprio 1
	v_mfma_f32_16x16x32_bf16 v[52:55], v[144:147], v[212:215], v[52:55]
	s_mov_b32 m0, s56
	v_mfma_f32_16x16x32_bf16 v[48:51], v[152:155], v[212:215], v[48:51]
	global_load_lds_dwordx4 v[198:199], off
	v_mfma_f32_16x16x32_bf16 v[36:39], v[144:147], v[220:223], v[36:39]
	v_mfma_f32_16x16x32_bf16 v[32:35], v[152:155], v[220:223], v[32:35]
	v_mfma_f32_16x16x32_bf16 v[20:23], v[144:147], v[228:231], v[20:23]
	v_mfma_f32_16x16x32_bf16 v[16:19], v[152:155], v[228:231], v[16:19]
	v_mfma_f32_16x16x32_bf16 v[68:71], v[148:151], v[194:197], v[68:71]
	v_mfma_f32_16x16x32_bf16 v[64:67], v[156:159], v[194:197], v[64:67]
	v_mfma_f32_16x16x32_bf16 v[52:55], v[148:151], v[216:219], v[52:55]
	s_mov_b32 m0, s57
	v_mfma_f32_16x16x32_bf16 v[48:51], v[156:159], v[216:219], v[48:51]
	global_load_lds_dwordx4 v[244:245], off
	v_mfma_f32_16x16x32_bf16 v[36:39], v[148:151], v[224:227], v[36:39]
	v_mfma_f32_16x16x32_bf16 v[32:35], v[156:159], v[224:227], v[32:35]
	v_mfma_f32_16x16x32_bf16 v[20:23], v[148:151], v[232:235], v[20:23]
	v_mfma_f32_16x16x32_bf16 v[16:19], v[156:159], v[232:235], v[16:19]
	s_setprio 0
	s_setprio 1
	v_mfma_f32_16x16x32_bf16 v[60:63], v[160:163], v[190:193], v[60:63]
	v_mfma_f32_16x16x32_bf16 v[56:59], v[182:185], v[190:193], v[56:59]
	v_mfma_f32_16x16x32_bf16 v[44:47], v[160:163], v[212:215], v[44:47]
	v_mfma_f32_16x16x32_bf16 v[40:43], v[182:185], v[212:215], v[40:43]
	v_mfma_f32_16x16x32_bf16 v[28:31], v[160:163], v[220:223], v[28:31]
	v_mfma_f32_16x16x32_bf16 v[24:27], v[182:185], v[220:223], v[24:27]
	v_mfma_f32_16x16x32_bf16 v[12:15], v[160:163], v[228:231], v[12:15]
	v_mfma_f32_16x16x32_bf16 v[8:11], v[182:185], v[228:231], v[8:11]
	v_mfma_f32_16x16x32_bf16 v[60:63], v[178:181], v[194:197], v[60:63]
	v_mfma_f32_16x16x32_bf16 v[56:59], v[186:189], v[194:197], v[56:59]
	v_mfma_f32_16x16x32_bf16 v[44:47], v[178:181], v[216:219], v[44:47]
	v_mfma_f32_16x16x32_bf16 v[40:43], v[186:189], v[216:219], v[40:43]
	v_mfma_f32_16x16x32_bf16 v[28:31], v[178:181], v[224:227], v[28:31]
	v_mfma_f32_16x16x32_bf16 v[24:27], v[186:189], v[224:227], v[24:27]
	s_barrier
	v_mfma_f32_16x16x32_bf16 v[12:15], v[178:181], v[232:235], v[12:15]
	v_mfma_f32_16x16x32_bf16 v[8:11], v[186:189], v[232:235], v[8:11]
	s_setprio 0
	s_add_u32 s24, s24, 0x100
	s_addc_u32 s25, s25, 0
	s_add_u32 s23, s23, 0x100
	s_addc_u32 s35, s35, 0
	s_cmp_ge_u32 s36, s59
	s_mov_b32 s28, s36
	s_cbranch_scc0 .LBB0_203
	s_and_b64 vcc, exec, s[46:47]
	s_cbranch_vccz .LBB0_206
	s_barrier
	s_setprio 1

; #define PG8_STAGE(bufoff, gbase, voff) do { _Pragma("unroll") for (int _i = 0; _i < 2; ++_i) \
;         __builtin_amdgcn_global_load_lds((const unsigned*)((const char*)(gbase) + (voff)[_i]), (PG8_LAS unsigned*)(lds + (bufoff) + ldsw + _i * 8192), 16, 0, 0); } while (0)
; #define PG8_LDA(dst, b, h) do { _Pragma("unroll") for (int m = 0; m < 4; ++m) _Pragma("unroll") for (int k = 0; k < 2; ++k) dst[m][k] = *(const PG8_LAS bf16x8*)(lds + PG8_SA(b, h) + aoff + m * 2048 + k * 1024); } while (0)
; #define PG8_LDB(dst, b, h) do { _Pragma("unroll") for (int n = 0; n < 2; ++n) _Pragma("unroll") for (int k = 0; k < 2; ++k) dst[n][k] = *(const PG8_LAS bf16x8*)(lds + PG8_SB(b, h) + boff + n * 2048 + k * 1024); } while (0)
; #define PG8_MMA(ai, bj, At, Bt) do { __builtin_amdgcn_s_setprio(1); _Pragma("unroll") for (int m = 0; m < 4; ++m) _Pragma("unroll") for (int n = 0; n < 2; ++n) _Pragma("unroll") for (int k = 0; k < 2; ++k) \
;         acc[ai][bj][m][n] = __builtin_amdgcn_mfma_f32_16x16x32_bf16(Bt[n][k], At[m][k], acc[ai][bj][m][n], 0, 0, 0); __builtin_amdgcn_s_setprio(0); } while (0)
; #define PG8_WAIT_V(n) asm volatile("s_waitcnt vmcnt(" #n ")" ::: "memory")
; #define PG8_WAIT_L(n) asm volatile("s_waitcnt lgkmcnt(" #n ")" ::: "memory")
; #define PG8_BAR __builtin_amdgcn_s_barrier()
; #define PG8_SCHED __builtin_amdgcn_sched_barrier(0)
; template <class Epi, class Sched, bool ALIGN_EPI = false, bool SP2 = false>
; __device__ __forceinline__ void gemm_phase(PG8_LAS unsigned char* lds, const Gemm g, const Sched& S, const Epi& E) {
;     ...
;             const bool last = (t == nt - 2);
;             const char* a1 = cA + (size_t)(t + 1) * kstep;
;             const char* a2 = last ? nA : cA + (size_t)(t + 2) * kstep; const char* b2 = last ? nB : cB + (size_t)(t + 2) * kstep;
;             const char* a3 = a2 + kstep; const char* b3 = b2 + kstep;
;             if (last && has_next) S.a_ready(nxt);
;             if constexpr (SP2) {
;             PG8_LDB(B0, 0, 0); PG8_LDB(B1, 0, 1); PG8_SCHED; PG8_LDA(At, 0, 0); PG8_STAGE(PG8_SA(1, 1), a1 + hstep, voffA);
;             PG8_WAIT_V(8); PG8_WAIT_L(0); PG8_BAR; PG8_MMA(0, 0, At, B0); PG8_MMA(0, 1, At, B1); PG8_BAR; PG8_SCHED;
;             PG8_LDA(At, 0, 1); PG8_STAGE(PG8_SB(0, 0), b2, voffB); PG8_STAGE(PG8_SB(0, 1), b2 + hstep, voffB); PG8_STAGE(PG8_SA(0, 0), a2, voffA);
.LBB0_257:
	s_add_u32 s16, s8, 0xfffc0080
	s_addc_u32 s17, s9, -1
	s_add_i32 s18, 0, 0x10000
	s_cmp_eq_u32 s55, 12
	s_cselect_b32 s43, s14, s17
	s_cselect_b32 s42, s15, s16
	v_add_u32_e32 v0, s18, v210
	s_cselect_b32 s41, s13, s54
	s_cselect_b32 s40, s25, s53
	s_add_i32 s19, 0, 0x14000
	ds_read_b128 v[104:107], v0
	ds_read_b128 v[140:143], v0 offset:1024
	ds_read_b128 v[144:147], v0 offset:2048
	ds_read_b128 v[148:151], v0 offset:3072
	v_add_u32_e32 v0, s19, v210
	ds_read_b128 v[152:155], v0
	ds_read_b128 v[156:159], v0 offset:1024
	ds_read_b128 v[160:163], v0 offset:2048
	ds_read_b128 v[192:195], v0 offset:3072
	v_lshl_add_u64 v[2:3], s[8:9], 0, v[188:189]
	s_add_i32 m0, s44, 0xc000
	ds_read_b128 v[196:199], v212
	ds_read_b128 v[214:217], v212 offset:1024
	ds_read_b128 v[218:221], v212 offset:2048
	ds_read_b128 v[222:225], v212 offset:3072
	ds_read_b128 v[226:229], v212 offset:4096
	ds_read_b128 v[230:233], v212 offset:5120
	ds_read_b128 v[234:237], v212 offset:6144
	ds_read_b128 v[238:241], v212 offset:7168
	global_load_lds_dwordx4 v[2:3], off
	v_lshl_add_u64 v[2:3], s[8:9], 0, v[190:191]
	s_add_i32 m0, s44, 0xe000
	s_nop 0
	global_load_lds_dwordx4 v[2:3], off
	s_waitcnt vmcnt(8)
	s_waitcnt lgkmcnt(0)
	s_barrier
	s_waitcnt lgkmcnt(0)
	v_mfma_f32_16x16x32_bf16 v[136:139], v[104:107], v[196:199], v[136:139]
	v_mfma_f32_16x16x32_bf16 v[128:131], v[144:147], v[196:199], v[128:131]
	s_setprio 1
	v_mfma_f32_16x16x32_bf16 v[120:123], v[104:107], v[218:221], v[120:123]
	v_mfma_f32_16x16x32_bf16 v[112:115], v[144:147], v[218:221], v[112:115]
	v_mfma_f32_16x16x32_bf16 v[100:103], v[104:107], v[226:229], v[100:103]
	v_mfma_f32_16x16x32_bf16 v[92:95], v[144:147], v[226:229], v[92:95]
	v_mfma_f32_16x16x32_bf16 v[84:87], v[104:107], v[234:237], v[84:87]
	v_mfma_f32_16x16x32_bf16 v[76:79], v[144:147], v[234:237], v[76:79]
	v_mfma_f32_16x16x32_bf16 v[136:139], v[140:143], v[214:217], v[136:139]
	v_mfma_f32_16x16x32_bf16 v[128:131], v[148:151], v[214:217], v[128:131]
	v_mfma_f32_16x16x32_bf16 v[120:123], v[140:143], v[222:225], v[120:123]
	v_mfma_f32_16x16x32_bf16 v[112:115], v[148:151], v[222:225], v[112:115]
	v_mfma_f32_16x16x32_bf16 v[100:103], v[140:143], v[230:233], v[100:103]
	v_mfma_f32_16x16x32_bf16 v[92:95], v[148:151], v[230:233], v[92:95]
	v_mfma_f32_16x16x32_bf16 v[84:87], v[140:143], v[238:241], v[84:87]
	v_mfma_f32_16x16x32_bf16 v[76:79], v[148:151], v[238:241], v[76:79]
	s_setprio 0
	s_setprio 1
	v_mfma_f32_16x16x32_bf16 v[132:135], v[152:155], v[196:199], v[132:135]
	v_mfma_f32_16x16x32_bf16 v[124:127], v[160:163], v[196:199], v[124:127]
	v_mfma_f32_16x16x32_bf16 v[116:119], v[152:155], v[218:221], v[116:119]
	v_mfma_f32_16x16x32_bf16 v[108:111], v[160:163], v[218:221], v[108:111]
	v_mfma_f32_16x16x32_bf16 v[96:99], v[152:155], v[226:229], v[96:99]
	v_mfma_f32_16x16x32_bf16 v[88:91], v[160:163], v[226:229], v[88:91]
	v_mfma_f32_16x16x32_bf16 v[80:83], v[152:155], v[234:237], v[80:83]
	v_mfma_f32_16x16x32_bf16 v[72:75], v[160:163], v[234:237], v[72:75]
	v_mfma_f32_16x16x32_bf16 v[132:135], v[156:159], v[214:217], v[132:135]
	v_mfma_f32_16x16x32_bf16 v[124:127], v[192:195], v[214:217], v[124:127]
	v_mfma_f32_16x16x32_bf16 v[116:119], v[156:159], v[222:225], v[116:119]
	v_mfma_f32_16x16x32_bf16 v[108:111], v[192:195], v[222:225], v[108:111]
	v_mfma_f32_16x16x32_bf16 v[96:99], v[156:159], v[230:233], v[96:99]
	v_mfma_f32_16x16x32_bf16 v[88:91], v[192:195], v[230:233], v[88:91]
	s_barrier
	v_mfma_f32_16x16x32_bf16 v[80:83], v[156:159], v[238:241], v[80:83]
	v_mfma_f32_16x16x32_bf16 v[72:75], v[192:195], v[238:241], v[72:75]
	s_setprio 0
	s_add_i32 s16, s18, s36
	v_lshl_add_u64 v[2:3], s[40:41], 0, v[182:183]
	s_mov_b32 m0, s16
	ds_read_b128 v[196:199], v212 offset:16384
	ds_read_b128 v[214:217], v212 offset:17408
	ds_read_b128 v[218:221], v212 offset:18432
	ds_read_b128 v[222:225], v212 offset:19456
	ds_read_b128 v[226:229], v212 offset:20480
	ds_read_b128 v[230:233], v212 offset:21504
	ds_read_b128 v[234:237], v212 offset:22528
	ds_read_b128 v[238:241], v212 offset:23552
	global_load_lds_dwordx4 v[2:3], off
	s_add_i32 m0, s16, 0x2000
	s_add_u32 s16, s40, 0x40000
	v_lshl_add_u64 v[200:201], s[40:41], 0, v[178:179]
	s_addc_u32 s17, s41, 0
	s_add_i32 s18, s19, s36
	global_load_lds_dwordx4 v[200:201], off
	v_lshl_add_u64 v[242:243], s[16:17], 0, v[182:183]
	s_mov_b32 m0, s18
	v_lshl_add_u64 v[244:245], s[42:43], 0, v[180:181]
	global_load_lds_dwordx4 v[242:243], off
	v_lshl_add_u64 v[242:243], s[16:17], 0, v[178:179]
	s_add_i32 m0, s18, 0x2000
	s_nop 0
	global_load_lds_dwordx4 v[242:243], off
	v_lshl_add_u64 v[242:243], s[42:43], 0, v[184:185]
	s_waitcnt vmcnt(6)
	s_waitcnt lgkmcnt(0)
	s_barrier
; #define PG8_STAGE(bufoff, gbase, voff) do { _Pragma("unroll") for (int _i = 0; _i < 2; ++_i) \
;         __builtin_amdgcn_global_load_lds((const unsigned*)((const char*)(gbase) + (voff)[_i]), (PG8_LAS unsigned*)(lds + (bufoff) + ldsw + _i * 8192), 16, 0, 0); } while (0)
; #define PG8_LDA(dst, b, h) do { _Pragma("unroll") for (int m = 0; m < 4; ++m) _Pragma("unroll") for (int k = 0; k < 2; ++k) dst[m][k] = *(const PG8_LAS bf16x8*)(lds + PG8_SA(b, h) + aoff + m * 2048 + k * 1024); } while (0)
; #define PG8_LDB(dst, b, h) do { _Pragma("unroll") for (int n = 0; n < 2; ++n) _Pragma("unroll") for (int k = 0; k < 2; ++k) dst[n][k] = *(const PG8_LAS bf16x8*)(lds + PG8_SB(b, h) + boff + n * 2048 + k * 1024); } while (0)
; #define PG8_MMA(ai, bj, At, Bt) do { __builtin_amdgcn_s_setprio(1); _Pragma("unroll") for (int m = 0; m < 4; ++m) _Pragma("unroll") for (int n = 0; n < 2; ++n) _Pragma("unroll") for (int k = 0; k < 2; ++k) \
;         acc[ai][bj][m][n] = __builtin_amdgcn_mfma_f32_16x16x32_bf16(Bt[n][k], At[m][k], acc[ai][bj][m][n], 0, 0, 0); __builtin_amdgcn_s_setprio(0); } while (0)
; #define PG8_WAIT_V(n) asm volatile("s_waitcnt vmcnt(" #n ")" ::: "memory")
; #define PG8_WAIT_L(n) asm volatile("s_waitcnt lgkmcnt(" #n ")" ::: "memory")
; #define PG8_BAR __builtin_amdgcn_s_barrier()
; #define PG8_SCHED __builtin_amdgcn_sched_barrier(0)
; template <class Epi, class Sched, bool ALIGN_EPI = false, bool SP2 = false>
; __device__ __forceinline__ void gemm_phase(PG8_LAS unsigned char* lds, const Gemm g, const Sched& S, const Epi& E) {
;     ...
;             PG8_WAIT_V(8); PG8_WAIT_L(0); PG8_BAR; PG8_MMA(1, 0, At, B0); PG8_MMA(1, 1, At, B1); PG8_BAR; PG8_SCHED;
;             PG8_LDB(B0, 1, 0); PG8_LDB(B1, 1, 1); PG8_SCHED; PG8_LDA(At, 1, 0); PG8_STAGE(PG8_SA(0, 1), a2 + hstep, voffA);
;             PG8_WAIT_V(8); PG8_WAIT_L(0); PG8_BAR; PG8_MMA(0, 0, At, B0); PG8_MMA(0, 1, At, B1); PG8_BAR; PG8_SCHED;
	s_waitcnt lgkmcnt(0)
	v_mfma_f32_16x16x32_bf16 v[68:71], v[104:107], v[196:199], v[68:71]
	v_mfma_f32_16x16x32_bf16 v[60:63], v[144:147], v[196:199], v[60:63]
	s_setprio 1
	v_mfma_f32_16x16x32_bf16 v[52:55], v[104:107], v[218:221], v[52:55]
	s_mov_b32 m0, s44
	v_mfma_f32_16x16x32_bf16 v[44:47], v[144:147], v[218:221], v[44:47]
	global_load_lds_dwordx4 v[242:243], off
	v_mfma_f32_16x16x32_bf16 v[36:39], v[104:107], v[226:229], v[36:39]
	v_mfma_f32_16x16x32_bf16 v[28:31], v[144:147], v[226:229], v[28:31]
	v_mfma_f32_16x16x32_bf16 v[20:23], v[104:107], v[234:237], v[20:23]
	v_mfma_f32_16x16x32_bf16 v[12:15], v[144:147], v[234:237], v[12:15]
	v_mfma_f32_16x16x32_bf16 v[68:71], v[140:143], v[214:217], v[68:71]
	v_mfma_f32_16x16x32_bf16 v[60:63], v[148:151], v[214:217], v[60:63]
	v_mfma_f32_16x16x32_bf16 v[52:55], v[140:143], v[222:225], v[52:55]
	s_mov_b32 m0, s45
	v_mfma_f32_16x16x32_bf16 v[44:47], v[148:151], v[222:225], v[44:47]
	global_load_lds_dwordx4 v[244:245], off
	v_mfma_f32_16x16x32_bf16 v[36:39], v[140:143], v[230:233], v[36:39]
	v_mfma_f32_16x16x32_bf16 v[28:31], v[148:151], v[230:233], v[28:31]
	v_mfma_f32_16x16x32_bf16 v[20:23], v[140:143], v[238:241], v[20:23]
	v_mfma_f32_16x16x32_bf16 v[12:15], v[148:151], v[238:241], v[12:15]
	s_setprio 0
	s_setprio 1
	v_mfma_f32_16x16x32_bf16 v[64:67], v[152:155], v[196:199], v[64:67]
	v_mfma_f32_16x16x32_bf16 v[56:59], v[160:163], v[196:199], v[56:59]
	v_mfma_f32_16x16x32_bf16 v[48:51], v[152:155], v[218:221], v[48:51]
	v_mfma_f32_16x16x32_bf16 v[40:43], v[160:163], v[218:221], v[40:43]
	v_mfma_f32_16x16x32_bf16 v[32:35], v[152:155], v[226:229], v[32:35]
	v_mfma_f32_16x16x32_bf16 v[24:27], v[160:163], v[226:229], v[24:27]
	v_mfma_f32_16x16x32_bf16 v[16:19], v[152:155], v[234:237], v[16:19]
	v_mfma_f32_16x16x32_bf16 v[8:11], v[160:163], v[234:237], v[8:11]
	v_mfma_f32_16x16x32_bf16 v[64:67], v[156:159], v[214:217], v[64:67]
	v_mfma_f32_16x16x32_bf16 v[56:59], v[192:195], v[214:217], v[56:59]
	v_mfma_f32_16x16x32_bf16 v[48:51], v[156:159], v[222:225], v[48:51]
	v_mfma_f32_16x16x32_bf16 v[40:43], v[192:195], v[222:225], v[40:43]
	v_mfma_f32_16x16x32_bf16 v[32:35], v[156:159], v[230:233], v[32:35]
	v_mfma_f32_16x16x32_bf16 v[24:27], v[192:195], v[230:233], v[24:27]
	s_barrier
	v_mfma_f32_16x16x32_bf16 v[16:19], v[156:159], v[238:241], v[16:19]
	v_mfma_f32_16x16x32_bf16 v[8:11], v[192:195], v[238:241], v[8:11]
	s_setprio 0
	s_add_i32 s18, 0, 0x18000
	v_add_u32_e32 v0, s18, v210
	ds_read_b128 v[104:107], v0
	ds_read_b128 v[140:143], v0 offset:1024
	ds_read_b128 v[144:147], v0 offset:2048
	ds_read_b128 v[148:151], v0 offset:3072
	v_add_u32_e32 v0, s33, v210
	ds_read_b128 v[152:155], v0
	ds_read_b128 v[156:159], v0 offset:1024
	ds_read_b128 v[160:163], v0 offset:2048
	ds_read_b128 v[192:195], v0 offset:3072
	s_add_u32 s16, s42, 0x40000
	s_addc_u32 s17, s43, 0
	s_mov_b32 m0, s46
	v_lshl_add_u64 v[246:247], s[16:17], 0, v[184:185]
	ds_read_b128 v[196:199], v212 offset:32768
	ds_read_b128 v[214:217], v212 offset:33792
	ds_read_b128 v[218:221], v212 offset:34816
	ds_read_b128 v[222:225], v212 offset:35840
	ds_read_b128 v[226:229], v212 offset:36864
	ds_read_b128 v[230:233], v212 offset:37888
	ds_read_b128 v[234:237], v212 offset:38912
	ds_read_b128 v[238:241], v212 offset:39936
	global_load_lds_dwordx4 v[246:247], off
	v_lshl_add_u64 v[246:247], s[16:17], 0, v[180:181]
	s_mov_b32 m0, s47
	s_nop 0
	global_load_lds_dwordx4 v[246:247], off
	s_waitcnt vmcnt(8)
	s_waitcnt lgkmcnt(0)
	s_barrier
	s_waitcnt lgkmcnt(0)
	v_mfma_f32_16x16x32_bf16 v[136:139], v[104:107], v[196:199], v[136:139]
	v_mfma_f32_16x16x32_bf16 v[128:131], v[144:147], v[196:199], v[128:131]
	s_setprio 1
	v_mfma_f32_16x16x32_bf16 v[120:123], v[104:107], v[218:221], v[120:123]
	v_mfma_f32_16x16x32_bf16 v[112:115], v[144:147], v[218:221], v[112:115]
	v_mfma_f32_16x16x32_bf16 v[100:103], v[104:107], v[226:229], v[100:103]
	v_mfma_f32_16x16x32_bf16 v[92:95], v[144:147], v[226:229], v[92:95]
	v_mfma_f32_16x16x32_bf16 v[84:87], v[104:107], v[234:237], v[84:87]
	v_mfma_f32_16x16x32_bf16 v[76:79], v[144:147], v[234:237], v[76:79]
	v_mfma_f32_16x16x32_bf16 v[136:139], v[140:143], v[214:217], v[136:139]
	v_mfma_f32_16x16x32_bf16 v[128:131], v[148:151], v[214:217], v[128:131]
	v_mfma_f32_16x16x32_bf16 v[120:123], v[140:143], v[222:225], v[120:123]
	v_mfma_f32_16x16x32_bf16 v[112:115], v[148:151], v[222:225], v[112:115]
	v_mfma_f32_16x16x32_bf16 v[100:103], v[140:143], v[230:233], v[100:103]
	v_mfma_f32_16x16x32_bf16 v[92:95], v[148:151], v[230:233], v[92:95]
	v_mfma_f32_16x16x32_bf16 v[84:87], v[140:143], v[238:241], v[84:87]
	v_mfma_f32_16x16x32_bf16 v[76:79], v[148:151], v[238:241], v[76:79]
	s_setprio 0
	s_setprio 1
	v_mfma_f32_16x16x32_bf16 v[132:135], v[152:155], v[196:199], v[132:135]
	v_mfma_f32_16x16x32_bf16 v[124:127], v[160:163], v[196:199], v[124:127]
	v_mfma_f32_16x16x32_bf16 v[116:119], v[152:155], v[218:221], v[116:119]
	v_mfma_f32_16x16x32_bf16 v[108:111], v[160:163], v[218:221], v[108:111]
	v_mfma_f32_16x16x32_bf16 v[96:99], v[152:155], v[226:229], v[96:99]
	v_mfma_f32_16x16x32_bf16 v[88:91], v[160:163], v[226:229], v[88:91]
	v_mfma_f32_16x16x32_bf16 v[80:83], v[152:155], v[234:237], v[80:83]
	v_mfma_f32_16x16x32_bf16 v[72:75], v[160:163], v[234:237], v[72:75]
	v_mfma_f32_16x16x32_bf16 v[132:135], v[156:159], v[214:217], v[132:135]
	v_mfma_f32_16x16x32_bf16 v[124:127], v[192:195], v[214:217], v[124:127]
	v_mfma_f32_16x16x32_bf16 v[116:119], v[156:159], v[222:225], v[116:119]
	v_mfma_f32_16x16x32_bf16 v[108:111], v[192:195], v[222:225], v[108:111]
	v_mfma_f32_16x16x32_bf16 v[96:99], v[156:159], v[230:233], v[96:99]
	v_mfma_f32_16x16x32_bf16 v[88:91], v[192:195], v[230:233], v[88:91]
	s_barrier
; #define PG8_STAGE(bufoff, gbase, voff) do { _Pragma("unroll") for (int _i = 0; _i < 2; ++_i) \
;         __builtin_amdgcn_global_load_lds((const unsigned*)((const char*)(gbase) + (voff)[_i]), (PG8_LAS unsigned*)(lds + (bufoff) + ldsw + _i * 8192), 16, 0, 0); } while (0)
; #define PG8_LDA(dst, b, h) do { _Pragma("unroll") for (int m = 0; m < 4; ++m) _Pragma("unroll") for (int k = 0; k < 2; ++k) dst[m][k] = *(const PG8_LAS bf16x8*)(lds + PG8_SA(b, h) + aoff + m * 2048 + k * 1024); } while (0)
; #define PG8_MMA(ai, bj, At, Bt) do { __builtin_amdgcn_s_setprio(1); _Pragma("unroll") for (int m = 0; m < 4; ++m) _Pragma("unroll") for (int n = 0; n < 2; ++n) _Pragma("unroll") for (int k = 0; k < 2; ++k) \
;         acc[ai][bj][m][n] = __builtin_amdgcn_mfma_f32_16x16x32_bf16(Bt[n][k], At[m][k], acc[ai][bj][m][n], 0, 0, 0); __builtin_amdgcn_s_setprio(0); } while (0)
; #define PG8_WAIT_V(n) asm volatile("s_waitcnt vmcnt(" #n ")" ::: "memory")
; #define PG8_WAIT_L(n) asm volatile("s_waitcnt lgkmcnt(" #n ")" ::: "memory")
; #define PG8_BAR __builtin_amdgcn_s_barrier()
; #define PG8_SCHED __builtin_amdgcn_sched_barrier(0)
; template <class Epi, class Sched, bool ALIGN_EPI = false, bool SP2 = false>
; __device__ __forceinline__ void gemm_phase(PG8_LAS unsigned char* lds, const Gemm g, const Sched& S, const Epi& E) {
;     ...
;             PG8_WAIT_V(8); PG8_WAIT_L(0); PG8_BAR; PG8_MMA(0, 0, At, B0); PG8_MMA(0, 1, At, B1); PG8_BAR; PG8_SCHED;
;             PG8_LDA(At, 1, 1); PG8_STAGE(PG8_SB(1, 0), b3, voffB); PG8_STAGE(PG8_SB(1, 1), b3 + hstep, voffB); PG8_STAGE(PG8_SA(1, 0), a3, voffA);
;             PG8_WAIT_V(8); PG8_WAIT_L(0); PG8_BAR; PG8_MMA(1, 0, At, B0); PG8_MMA(1, 1, At, B1); PG8_BAR; PG8_SCHED;
	v_mfma_f32_16x16x32_bf16 v[80:83], v[156:159], v[238:241], v[80:83]
	v_mfma_f32_16x16x32_bf16 v[72:75], v[192:195], v[238:241], v[72:75]
	s_setprio 0
	s_add_i32 s16, s18, s36
	v_lshl_add_u64 v[2:3], v[2:3], 0, s[20:21]
	s_mov_b32 m0, s16
	ds_read_b128 v[196:199], v212 offset:49152
	ds_read_b128 v[214:217], v212 offset:50176
	ds_read_b128 v[218:221], v212 offset:51200
	ds_read_b128 v[222:225], v212 offset:52224
	ds_read_b128 v[226:229], v212 offset:53248
	ds_read_b128 v[230:233], v212 offset:54272
	ds_read_b128 v[234:237], v212 offset:55296
	ds_read_b128 v[238:241], v212 offset:56320
	global_load_lds_dwordx4 v[2:3], off
	s_add_i32 m0, s16, 0x2000
	s_add_u32 s16, s40, 0x40080
	v_lshl_add_u64 v[2:3], v[200:201], 0, s[20:21]
	s_addc_u32 s17, s41, 0
	s_add_i32 s18, s33, s36
	global_load_lds_dwordx4 v[2:3], off
	v_lshl_add_u64 v[2:3], s[16:17], 0, v[182:183]
	s_mov_b32 m0, s18
	s_nop 0
	global_load_lds_dwordx4 v[2:3], off
	v_lshl_add_u64 v[2:3], s[16:17], 0, v[178:179]
	s_add_i32 m0, s18, 0x2000
	s_nop 0
	global_load_lds_dwordx4 v[2:3], off
	v_lshl_add_u64 v[2:3], v[242:243], 0, s[20:21]
	v_lshl_add_u64 v[244:245], v[244:245], 0, s[20:21]
	s_waitcnt vmcnt(6)
	s_waitcnt lgkmcnt(0)
	s_barrier
	s_waitcnt lgkmcnt(0)
	v_mfma_f32_16x16x32_bf16 v[68:71], v[104:107], v[196:199], v[68:71]
	v_mfma_f32_16x16x32_bf16 v[60:63], v[144:147], v[196:199], v[60:63]
	s_setprio 1
	v_mfma_f32_16x16x32_bf16 v[52:55], v[104:107], v[218:221], v[52:55]
	s_mov_b32 m0, s48
	v_mfma_f32_16x16x32_bf16 v[44:47], v[144:147], v[218:221], v[44:47]
	global_load_lds_dwordx4 v[2:3], off
	v_mfma_f32_16x16x32_bf16 v[36:39], v[104:107], v[226:229], v[36:39]
	v_mfma_f32_16x16x32_bf16 v[28:31], v[144:147], v[226:229], v[28:31]
	v_mfma_f32_16x16x32_bf16 v[20:23], v[104:107], v[234:237], v[20:23]
	v_mfma_f32_16x16x32_bf16 v[12:15], v[144:147], v[234:237], v[12:15]
	v_mfma_f32_16x16x32_bf16 v[68:71], v[140:143], v[214:217], v[68:71]
	v_mfma_f32_16x16x32_bf16 v[60:63], v[148:151], v[214:217], v[60:63]
	v_mfma_f32_16x16x32_bf16 v[52:55], v[140:143], v[222:225], v[52:55]
	s_mov_b32 m0, s49
	v_mfma_f32_16x16x32_bf16 v[44:47], v[148:151], v[222:225], v[44:47]
	global_load_lds_dwordx4 v[244:245], off
	v_mfma_f32_16x16x32_bf16 v[36:39], v[140:143], v[230:233], v[36:39]
	v_mfma_f32_16x16x32_bf16 v[28:31], v[148:151], v[230:233], v[28:31]
	v_mfma_f32_16x16x32_bf16 v[20:23], v[140:143], v[238:241], v[20:23]
	v_mfma_f32_16x16x32_bf16 v[12:15], v[148:151], v[238:241], v[12:15]
	s_setprio 0
	s_setprio 1
	v_mfma_f32_16x16x32_bf16 v[64:67], v[152:155], v[196:199], v[64:67]
	v_mfma_f32_16x16x32_bf16 v[56:59], v[160:163], v[196:199], v[56:59]
	v_mfma_f32_16x16x32_bf16 v[48:51], v[152:155], v[218:221], v[48:51]
	v_mfma_f32_16x16x32_bf16 v[40:43], v[160:163], v[218:221], v[40:43]
	v_mfma_f32_16x16x32_bf16 v[32:35], v[152:155], v[226:229], v[32:35]
	v_mfma_f32_16x16x32_bf16 v[24:27], v[160:163], v[226:229], v[24:27]
	v_mfma_f32_16x16x32_bf16 v[16:19], v[152:155], v[234:237], v[16:19]
	v_mfma_f32_16x16x32_bf16 v[8:11], v[160:163], v[234:237], v[8:11]
	v_mfma_f32_16x16x32_bf16 v[64:67], v[156:159], v[214:217], v[64:67]
	v_mfma_f32_16x16x32_bf16 v[56:59], v[192:195], v[214:217], v[56:59]
	v_mfma_f32_16x16x32_bf16 v[48:51], v[156:159], v[222:225], v[48:51]
	v_mfma_f32_16x16x32_bf16 v[40:43], v[192:195], v[222:225], v[40:43]
	v_mfma_f32_16x16x32_bf16 v[32:35], v[156:159], v[230:233], v[32:35]
	v_mfma_f32_16x16x32_bf16 v[24:27], v[192:195], v[230:233], v[24:27]
	s_barrier
	v_mfma_f32_16x16x32_bf16 v[16:19], v[156:159], v[238:241], v[16:19]
	v_mfma_f32_16x16x32_bf16 v[8:11], v[192:195], v[238:241], v[8:11]
	s_setprio 0
	s_add_i32 s55, s55, 2
	s_add_u32 s8, s8, 0x100
	s_addc_u32 s9, s9, 0
	s_add_u32 s53, s53, 0x100
	s_addc_u32 s54, s54, 0
	s_cmp_gt_u32 s55, 13
	s_cbranch_scc0 .LBB0_257
	s_and_b64 vcc, exec, s[10:11]
	s_cbranch_vccz .LBB0_260
	s_barrier
	s_setprio 1
